# v10 + GEMM unit headers: exact specialised StaticOrder::next (gsz is always 4 since nM=128: shifts/masks + one magic multiply, ~17 scalar ops) replaces the generic ~70-op runtime-division index math i
# speedup vs baseline: 1.0016x; 1.0016x over previous
.LBB0_157:
	s_add_i32 s24, s24, 1
	v_readlane_b32 s13, v252, 2
	v_readlane_b32 s20, v254, 0
	s_nop 0
	s_mul_i32 s8, s24, s13
	s_add_i32 s8, s8, s20
	s_cmpk_lt_u32 s8, 0xc00
	s_cselect_b64 s[40:41], -1, 0
	s_and_b32 s9, s8, 7
	s_mulk_i32 s9, 0x180
	s_lshr_b32 s19, s8, 3
	s_add_i32 s9, s9, s19
	s_mul_hi_u32 s19, s9, 0x2aaaaab
	s_mul_i32 s8, s19, 0x60
	s_sub_i32 s9, s9, s8
	s_lshl_b32 s19, s19, 2
	s_lshr_b32 s18, s9, 2
	s_and_b32 s9, s9, 3
	s_add_i32 s22, s19, s9

.LBB0_893:
	s_add_i32 s64, s9, 1
	s_mul_hi_u32 s18, s64, 0xaaaaaaab
	s_lshr_b32 s20, s18, 2
	v_readlane_b32 s18, v252, 2
	v_readlane_b32 s19, v254, 0
	s_nop 0
	s_mul_i32 s21, s20, s18
	s_add_i32 s21, s21, s19
	s_cmpk_lt_u32 s21, 0x400
	s_cselect_b64 s[40:41], -1, 0
	s_and_b32 s24, s21, 7
	s_mulk_i32 s24, 0x80
	s_lshr_b32 s25, s21, 3
	s_add_i32 s24, s24, s25
	s_lshr_b32 s25, s24, 5
	s_and_b32 s24, s24, 31
	s_lshl_b32 s25, s25, 2
	s_lshr_b32 s42, s24, 2
	s_and_b32 s24, s24, 3
	s_add_i32 s44, s25, s24

.LBB0_1016:
	s_add_i32 s56, s56, 1
	v_readlane_b32 s19, v252, 2
	v_readlane_b32 s20, v254, 0
	s_nop 0
	s_mul_i32 s12, s56, s19
	s_add_i32 s12, s12, s20
	s_cmpk_lt_u32 s12, 0x400
	s_cselect_b64 s[38:39], -1, 0
	s_and_b32 s13, s12, 7
	s_mulk_i32 s13, 0x80
	s_lshr_b32 s21, s12, 3
	s_add_i32 s13, s13, s21
	s_lshr_b32 s21, s13, 5
	s_and_b32 s13, s13, 31
	s_lshl_b32 s21, s21, 2
	s_lshr_b32 s18, s13, 2
	s_and_b32 s13, s13, 3
	s_add_i32 s22, s21, s13

.LBB0_1111:
	s_add_i32 s53, s53, 1
	v_readlane_b32 s19, v252, 2
	v_readlane_b32 s20, v254, 0
	s_nop 0
	s_mul_i32 s22, s53, s19
	s_add_i32 s22, s22, s20
	s_cmpk_lt_u32 s22, 0x1600
	s_cselect_b64 s[38:39], -1, 0
	s_and_b32 s11, s22, 7
	s_mulk_i32 s11, 0x2c0
	s_lshr_b32 s13, s22, 3
	s_add_i32 s11, s11, s13
	s_mul_hi_u32 s13, s11, 0x1745d18
	s_mul_i32 s22, s13, 0xb0
	s_sub_i32 s11, s11, s22
	s_lshl_b32 s13, s13, 2
	s_lshr_b32 s10, s11, 2
	s_and_b32 s11, s11, 3
	s_add_i32 s18, s13, s11

.LBB0_1184:
	s_add_i32 s50, s50, 1
	v_readlane_b32 s22, v252, 2
	v_readlane_b32 s23, v254, 0
	s_nop 0
	s_mul_i32 s20, s50, s22
	s_add_i32 s20, s20, s23
	s_cmpk_lt_u32 s20, 0x400
	s_cselect_b64 s[40:41], -1, 0
	s_and_b32 s21, s20, 7
	s_mulk_i32 s21, 0x80
	s_lshr_b32 s24, s20, 3
	s_add_i32 s21, s21, s24
	s_lshr_b32 s24, s21, 5
	s_and_b32 s21, s21, 31
	s_lshl_b32 s24, s24, 2
	s_lshr_b32 s55, s21, 2
	s_and_b32 s21, s21, 3
	s_add_i32 s56, s24, s21
